# same as previous with a small-grid guard in the prologue remap
# speedup vs baseline: 1.0052x; 1.0019x over previous
; #define FIN(i) ((const float*)(const GAS float*)(((const float* const __attribute__((address_space(4)))*)__builtin_amdgcn_kernarg_segment_ptr())[i]))
; __device__ __forceinline__ void phase_prologue(Frame& F) {
;     ...
;     for (int it = F.gw * 64 + lane; it < 2 * 4096; it += F.ngw * 64) {
;         const int l = it >> 12, g = (it >> 6) & 63, n = it & 63;
;         const double dt = exp_d((double)FIN(IN_LSTEP)[l * 64 + g]);
;         const double lr = (double)FIN(IN_LRE)[(l * 64 + g) * 64 + n], li = (double)FIN(IN_LIM)[(l * 64 + g) * 64 + n];
;         const double mag = exp_d(lr * dt); double sn, cs; sincos_d(li * dt, sn, cs);
.LBB0_74:
	v_writelane_b32 v252, s66, 10
	s_mov_b32 s80, s92
	s_sub_i32 s15, s88, s14
	s_add_i32 s15, s15, 0xffffffbf
	s_cmp_lt_i32 s15, 0
	s_cselect_b32 s15, 0x7fff, s15
	s_cmpk_lt_i32 s88, 0xc1
	s_cselect_b32 s15, s14, s15
	v_lshl_or_b32 v3, s15, 6, v1
	v_writelane_b32 v252, s67, 11
	s_movk_i32 s4, 0x2000
	s_lshl_b32 s91, s84, 9
	v_lshlrev_b32_e32 v2, 4, v1
	v_cmp_gt_i32_e32 vcc, s4, v3
	s_mov_b64 s[4:5], exec
	v_writelane_b32 v252, s4, 12
	s_nop 1
	v_writelane_b32 v252, s5, 13
	s_and_b64 s[4:5], s[4:5], vcc
	s_mov_b64 exec, s[4:5]
	s_cbranch_execz .LBB0_83
	v_readlane_b32 s4, v252, 10
	v_readlane_b32 s5, v252, 11
	s_add_u32 s34, s4, 0xa100000
	s_addc_u32 s35, s5, 0
	s_add_u32 s36, s4, 0xa300000
	s_addc_u32 s37, s5, 0
	s_add_u32 s38, s4, 0x2b700000
	s_addc_u32 s39, s5, 0
	s_add_u32 s40, s4, 0xa500000
	s_addc_u32 s41, s5, 0
	s_load_dwordx8 s[16:23], s[0:1], 0x70
	s_load_dwordx4 s[4:7], s[0:1], 0x90
	s_waitcnt lgkmcnt(0)
	s_load_dwordx2 s[4:5], s[0:1], 0xa0
	v_mov_b32_e32 v5, 0
	v_mov_b32_e32 v69, v5
	s_lshl_b32 s3, s3, 6
	v_lshlrev_b32_e32 v4, 1, v1
	s_waitcnt lgkmcnt(0)
	v_lshl_add_u64 v[8:9], s[4:5], 0, v[68:69]
	s_lshl_b32 s4, s15, 6
	v_or_b32_e32 v10, s4, v1
	s_mov_b32 s42, 0
	s_mov_b32 s44, 0
	s_mov_b32 s46, 0
	s_mov_b32 s48, 0
	s_mov_b32 s50, 0
	s_mov_b32 s52, 0
	s_mov_b32 s54, 0
	s_mov_b32 s56, 0
	s_mov_b32 s58, 0
	s_mov_b32 s60, 0
	s_mov_b32 s62, 0
	s_mov_b32 s70, 0
	s_mov_b32 s72, 0
	s_mov_b32 s74, 0
	s_mov_b32 s76, 0
	s_mov_b32 s86, 0
	s_mov_b32 s24, 0
	s_mov_b32 s92, 0
	s_mov_b32 s94, 0
	s_mov_b32 s96, 0
	s_mov_b32 s30, 0
	s_mov_b32 s4, 0
	s_mov_b32 s28, 0
	s_mov_b32 s64, 0
	s_mov_b32 s66, 0
	s_mov_b32 s68, 0
	v_lshl_add_u64 v[6:7], s[6:7], 0, v[68:69]
	v_lshlrev_b32_e32 v30, 2, v10
	s_lshl_b32 s3, s84, 11
	s_mov_b64 s[26:27], 0
	s_mov_b32 s43, 0x3f900000
	s_mov_b32 s45, 0x40080000
	s_mov_b32 s47, 0x40140000
	s_mov_b32 s49, 0x40180000
	s_mov_b32 s51, 0x401c0000
	s_mov_b32 s53, 0x40220000
	s_mov_b32 s55, 0x40240000
	s_mov_b32 s57, 0x40260000
	s_mov_b32 s59, 0x40280000
	s_mov_b32 s61, 0x402a0000
	s_mov_b32 s63, 0x402c0000
	s_mov_b32 s71, 0x40340000
	s_mov_b32 s73, 0x40450000
	s_mov_b32 s75, 0x403e0000
	s_mov_b32 s77, 0x40520000
	s_mov_b32 s87, 0x404c0000
	s_mov_b32 s25, 0x405b8000
	s_mov_b32 s93, 0x40568000
	s_mov_b32 s95, 0x40638000
	s_mov_b32 s97, 0x40608000
	s_mov_b32 s31, 0x406a4000
	s_mov_b32 s5, 0x4066c000
	s_mov_b32 s29, 0x40710000
	s_mov_b32 s65, 0x406e0000
	s_mov_b32 s67, 0x40756000
	s_mov_b32 s69, 0x40732000
	v_lshlrev_b32_e32 v10, 1, v4
	s_branch .LBB0_78
